# speedup vs baseline: 1.0060x; 1.0060x over previous
.LBB0_187:
	s_add_u32 m0, s35, 0xc000
	ds_read_b128 v[176:179], v164
	ds_read_b128 v[180:183], v164 offset:1024
	ds_read_b128 v[184:187], v164 offset:2048
	ds_read_b128 v[188:191], v164 offset:3072
	ds_read_b128 v[192:195], v162
	ds_read_b128 v[196:199], v162 offset:1024
	ds_read_b128 v[200:203], v162 offset:2048
	ds_read_b128 v[204:207], v162 offset:3072
	ds_read_b128 v[208:211], v162 offset:4096
	ds_read_b128 v[212:215], v162 offset:5120
	ds_read_b128 v[216:219], v162 offset:6144
	ds_read_b128 v[220:223], v162 offset:7168
	global_load_lds_dwordx4 v128, s[76:77]
	s_add_u32 m0, s35, 0xe000
	s_nop 0
	global_load_lds_dwordx4 v130, s[76:77]
	s_add_u32 s76, s76, 0x80
	s_addc_u32 s77, s77, 0
	s_waitcnt lgkmcnt(8)
	s_barrier
	s_waitcnt lgkmcnt(0)
	s_setprio 1
	v_mfma_f32_16x16x32_bf16 v[124:127], v[176:179], v[192:195], v[124:127]
	v_mfma_f32_16x16x32_bf16 v[120:123], v[184:187], v[192:195], v[120:123]
	v_mfma_f32_16x16x32_bf16 v[116:119], v[176:179], v[200:203], v[116:119]
	v_mfma_f32_16x16x32_bf16 v[112:115], v[184:187], v[200:203], v[112:115]
	v_mfma_f32_16x16x32_bf16 v[108:111], v[176:179], v[208:211], v[108:111]
	v_mfma_f32_16x16x32_bf16 v[104:107], v[184:187], v[208:211], v[104:107]
	v_mfma_f32_16x16x32_bf16 v[100:103], v[176:179], v[216:219], v[100:103]
	v_mfma_f32_16x16x32_bf16 v[96:99], v[184:187], v[216:219], v[96:99]
	v_mfma_f32_16x16x32_bf16 v[124:127], v[180:183], v[196:199], v[124:127]
	v_mfma_f32_16x16x32_bf16 v[120:123], v[188:191], v[196:199], v[120:123]
	v_mfma_f32_16x16x32_bf16 v[116:119], v[180:183], v[204:207], v[116:119]
	v_mfma_f32_16x16x32_bf16 v[112:115], v[188:191], v[204:207], v[112:115]
	v_mfma_f32_16x16x32_bf16 v[108:111], v[180:183], v[212:215], v[108:111]
	v_mfma_f32_16x16x32_bf16 v[104:107], v[188:191], v[212:215], v[104:107]
	v_mfma_f32_16x16x32_bf16 v[100:103], v[180:183], v[220:223], v[100:103]
	v_mfma_f32_16x16x32_bf16 v[96:99], v[188:191], v[220:223], v[96:99]
	s_setprio 0
	s_barrier
	s_add_u32 m0, s35, 0x10000
	ds_read_b128 v[224:227], v164 offset:16384
	ds_read_b128 v[228:231], v164 offset:17408
	ds_read_b128 v[232:235], v164 offset:18432
	ds_read_b128 v[236:239], v164 offset:19456
	global_load_lds_dwordx4 v128, s[42:43]
	s_add_u32 m0, s35, 0x12000
	s_nop 0
	global_load_lds_dwordx4 v130, s[42:43]
	s_add_u32 s42, s42, 0x80
	s_addc_u32 s43, s43, 0
	s_add_i32 s34, s34, 2
	s_barrier
	s_waitcnt lgkmcnt(0)
	s_setprio 1
	v_mfma_f32_16x16x32_bf16 v[92:95], v[224:227], v[192:195], v[92:95]
	v_mfma_f32_16x16x32_bf16 v[88:91], v[232:235], v[192:195], v[88:91]
	v_mfma_f32_16x16x32_bf16 v[84:87], v[224:227], v[200:203], v[84:87]
	v_mfma_f32_16x16x32_bf16 v[80:83], v[232:235], v[200:203], v[80:83]
	v_mfma_f32_16x16x32_bf16 v[76:79], v[224:227], v[208:211], v[76:79]
	v_mfma_f32_16x16x32_bf16 v[72:75], v[232:235], v[208:211], v[72:75]
	v_mfma_f32_16x16x32_bf16 v[68:71], v[224:227], v[216:219], v[68:71]
	v_mfma_f32_16x16x32_bf16 v[64:67], v[232:235], v[216:219], v[64:67]
	v_mfma_f32_16x16x32_bf16 v[92:95], v[228:231], v[196:199], v[92:95]
	v_mfma_f32_16x16x32_bf16 v[88:91], v[236:239], v[196:199], v[88:91]
	v_mfma_f32_16x16x32_bf16 v[84:87], v[228:231], v[204:207], v[84:87]
	v_mfma_f32_16x16x32_bf16 v[80:83], v[236:239], v[204:207], v[80:83]
	v_mfma_f32_16x16x32_bf16 v[76:79], v[228:231], v[212:215], v[76:79]
	v_mfma_f32_16x16x32_bf16 v[72:75], v[236:239], v[212:215], v[72:75]
	v_mfma_f32_16x16x32_bf16 v[68:71], v[228:231], v[220:223], v[68:71]
	v_mfma_f32_16x16x32_bf16 v[64:67], v[236:239], v[220:223], v[64:67]
	s_setprio 0
	s_barrier
	s_add_u32 m0, s35, 0x0
	ds_read_b128 v[192:195], v162 offset:16384
	ds_read_b128 v[196:199], v162 offset:17408
	ds_read_b128 v[200:203], v162 offset:18432
	ds_read_b128 v[204:207], v162 offset:19456
	ds_read_b128 v[208:211], v162 offset:20480
	ds_read_b128 v[212:215], v162 offset:21504
	ds_read_b128 v[216:219], v162 offset:22528
	ds_read_b128 v[220:223], v162 offset:23552
	global_load_lds_dwordx4 v128, s[72:73]
	s_add_u32 m0, s35, 0x2000
	s_nop 0
	global_load_lds_dwordx4 v130, s[72:73]
	s_add_u32 s72, s72, 0x80
	s_addc_u32 s73, s73, 0
	s_barrier
	s_waitcnt lgkmcnt(0)
	s_setprio 1
	v_mfma_f32_16x16x32_bf16 v[60:63], v[176:179], v[192:195], v[60:63]
	v_mfma_f32_16x16x32_bf16 v[56:59], v[184:187], v[192:195], v[56:59]
	v_mfma_f32_16x16x32_bf16 v[52:55], v[176:179], v[200:203], v[52:55]
	v_mfma_f32_16x16x32_bf16 v[48:51], v[184:187], v[200:203], v[48:51]
	v_mfma_f32_16x16x32_bf16 v[44:47], v[176:179], v[208:211], v[44:47]
	v_mfma_f32_16x16x32_bf16 v[40:43], v[184:187], v[208:211], v[40:43]
	v_mfma_f32_16x16x32_bf16 v[36:39], v[176:179], v[216:219], v[36:39]
	v_mfma_f32_16x16x32_bf16 v[32:35], v[184:187], v[216:219], v[32:35]
	v_mfma_f32_16x16x32_bf16 v[60:63], v[180:183], v[196:199], v[60:63]
	v_mfma_f32_16x16x32_bf16 v[56:59], v[188:191], v[196:199], v[56:59]
	v_mfma_f32_16x16x32_bf16 v[52:55], v[180:183], v[204:207], v[52:55]
	v_mfma_f32_16x16x32_bf16 v[48:51], v[188:191], v[204:207], v[48:51]
	v_mfma_f32_16x16x32_bf16 v[44:47], v[180:183], v[212:215], v[44:47]
	v_mfma_f32_16x16x32_bf16 v[40:43], v[188:191], v[212:215], v[40:43]
	v_mfma_f32_16x16x32_bf16 v[36:39], v[180:183], v[220:223], v[36:39]
	v_mfma_f32_16x16x32_bf16 v[32:35], v[188:191], v[220:223], v[32:35]
	s_setprio 0
	s_barrier
	s_add_u32 m0, s35, 0x14000
	s_nop 0
	global_load_lds_dwordx4 v128, s[78:79]
	s_add_u32 m0, s35, 0x16000
	s_nop 0
	global_load_lds_dwordx4 v130, s[78:79]
	s_add_u32 s78, s78, 0x80
	s_addc_u32 s79, s79, 0
	s_waitcnt vmcnt(6)
	s_barrier
	s_setprio 1
	v_mfma_f32_16x16x32_bf16 v[28:31], v[224:227], v[192:195], v[28:31]
	v_mfma_f32_16x16x32_bf16 v[24:27], v[232:235], v[192:195], v[24:27]
	v_mfma_f32_16x16x32_bf16 v[20:23], v[224:227], v[200:203], v[20:23]
	v_mfma_f32_16x16x32_bf16 v[16:19], v[232:235], v[200:203], v[16:19]
	v_mfma_f32_16x16x32_bf16 v[12:15], v[224:227], v[208:211], v[12:15]
	v_mfma_f32_16x16x32_bf16 v[8:11], v[232:235], v[208:211], v[8:11]
	v_mfma_f32_16x16x32_bf16 v[4:7], v[224:227], v[216:219], v[4:7]
	v_mfma_f32_16x16x32_bf16 v[0:3], v[232:235], v[216:219], v[0:3]
	v_mfma_f32_16x16x32_bf16 v[28:31], v[228:231], v[196:199], v[28:31]
	v_mfma_f32_16x16x32_bf16 v[24:27], v[236:239], v[196:199], v[24:27]
	v_mfma_f32_16x16x32_bf16 v[20:23], v[228:231], v[204:207], v[20:23]
	v_mfma_f32_16x16x32_bf16 v[16:19], v[236:239], v[204:207], v[16:19]
	v_mfma_f32_16x16x32_bf16 v[12:15], v[228:231], v[212:215], v[12:15]
	v_mfma_f32_16x16x32_bf16 v[8:11], v[236:239], v[212:215], v[8:11]
	v_mfma_f32_16x16x32_bf16 v[4:7], v[228:231], v[220:223], v[4:7]
	v_mfma_f32_16x16x32_bf16 v[0:3], v[236:239], v[220:223], v[0:3]
	s_setprio 0
	s_barrier
	s_add_u32 m0, s35, 0x4000
	ds_read_b128 v[176:179], v164 offset:32768
	ds_read_b128 v[180:183], v164 offset:33792
	ds_read_b128 v[184:187], v164 offset:34816
	ds_read_b128 v[188:191], v164 offset:35840
	ds_read_b128 v[192:195], v162 offset:32768
	ds_read_b128 v[196:199], v162 offset:33792
	ds_read_b128 v[200:203], v162 offset:34816
	ds_read_b128 v[204:207], v162 offset:35840
	ds_read_b128 v[208:211], v162 offset:36864
	ds_read_b128 v[212:215], v162 offset:37888
	ds_read_b128 v[216:219], v162 offset:38912
	ds_read_b128 v[220:223], v162 offset:39936
	global_load_lds_dwordx4 v128, s[76:77]
	s_add_u32 m0, s35, 0x6000
	s_nop 0
	global_load_lds_dwordx4 v130, s[76:77]
	s_add_u32 s76, s76, 0x80
	s_addc_u32 s77, s77, 0
	s_waitcnt lgkmcnt(8)
	s_barrier
	s_waitcnt lgkmcnt(0)
	s_setprio 1
	v_mfma_f32_16x16x32_bf16 v[124:127], v[176:179], v[192:195], v[124:127]
	v_mfma_f32_16x16x32_bf16 v[120:123], v[184:187], v[192:195], v[120:123]
	v_mfma_f32_16x16x32_bf16 v[116:119], v[176:179], v[200:203], v[116:119]
	v_mfma_f32_16x16x32_bf16 v[112:115], v[184:187], v[200:203], v[112:115]
	v_mfma_f32_16x16x32_bf16 v[108:111], v[176:179], v[208:211], v[108:111]
	v_mfma_f32_16x16x32_bf16 v[104:107], v[184:187], v[208:211], v[104:107]
	v_mfma_f32_16x16x32_bf16 v[100:103], v[176:179], v[216:219], v[100:103]
	v_mfma_f32_16x16x32_bf16 v[96:99], v[184:187], v[216:219], v[96:99]
	v_mfma_f32_16x16x32_bf16 v[124:127], v[180:183], v[196:199], v[124:127]
	v_mfma_f32_16x16x32_bf16 v[120:123], v[188:191], v[196:199], v[120:123]
	v_mfma_f32_16x16x32_bf16 v[116:119], v[180:183], v[204:207], v[116:119]
	v_mfma_f32_16x16x32_bf16 v[112:115], v[188:191], v[204:207], v[112:115]
	v_mfma_f32_16x16x32_bf16 v[108:111], v[180:183], v[212:215], v[108:111]
	v_mfma_f32_16x16x32_bf16 v[104:107], v[188:191], v[212:215], v[104:107]
	v_mfma_f32_16x16x32_bf16 v[100:103], v[180:183], v[220:223], v[100:103]
	v_mfma_f32_16x16x32_bf16 v[96:99], v[188:191], v[220:223], v[96:99]
	s_setprio 0
	s_barrier
	s_add_u32 m0, s35, 0x18000
	ds_read_b128 v[224:227], v164 offset:49152
	ds_read_b128 v[228:231], v164 offset:50176
	ds_read_b128 v[232:235], v164 offset:51200
	ds_read_b128 v[236:239], v164 offset:52224
	global_load_lds_dwordx4 v128, s[42:43]
	s_add_u32 m0, s35, 0x1a000
	s_nop 0
	global_load_lds_dwordx4 v130, s[42:43]
	s_add_u32 s42, s42, 0x80
	s_addc_u32 s43, s43, 0
	s_barrier
	s_waitcnt lgkmcnt(0)
	s_setprio 1
	v_mfma_f32_16x16x32_bf16 v[92:95], v[224:227], v[192:195], v[92:95]
	v_mfma_f32_16x16x32_bf16 v[88:91], v[232:235], v[192:195], v[88:91]
	v_mfma_f32_16x16x32_bf16 v[84:87], v[224:227], v[200:203], v[84:87]
	v_mfma_f32_16x16x32_bf16 v[80:83], v[232:235], v[200:203], v[80:83]
	v_mfma_f32_16x16x32_bf16 v[76:79], v[224:227], v[208:211], v[76:79]
	v_mfma_f32_16x16x32_bf16 v[72:75], v[232:235], v[208:211], v[72:75]
	v_mfma_f32_16x16x32_bf16 v[68:71], v[224:227], v[216:219], v[68:71]
	v_mfma_f32_16x16x32_bf16 v[64:67], v[232:235], v[216:219], v[64:67]
	v_mfma_f32_16x16x32_bf16 v[92:95], v[228:231], v[196:199], v[92:95]
	v_mfma_f32_16x16x32_bf16 v[88:91], v[236:239], v[196:199], v[88:91]
	v_mfma_f32_16x16x32_bf16 v[84:87], v[228:231], v[204:207], v[84:87]
	v_mfma_f32_16x16x32_bf16 v[80:83], v[236:239], v[204:207], v[80:83]
	v_mfma_f32_16x16x32_bf16 v[76:79], v[228:231], v[212:215], v[76:79]
	v_mfma_f32_16x16x32_bf16 v[72:75], v[236:239], v[212:215], v[72:75]
	v_mfma_f32_16x16x32_bf16 v[68:71], v[228:231], v[220:223], v[68:71]
	v_mfma_f32_16x16x32_bf16 v[64:67], v[236:239], v[220:223], v[64:67]
	s_setprio 0
	s_barrier
	s_add_u32 m0, s35, 0x8000
	ds_read_b128 v[192:195], v162 offset:49152
	ds_read_b128 v[196:199], v162 offset:50176
	ds_read_b128 v[200:203], v162 offset:51200
	ds_read_b128 v[204:207], v162 offset:52224
	ds_read_b128 v[208:211], v162 offset:53248
	ds_read_b128 v[212:215], v162 offset:54272
	ds_read_b128 v[216:219], v162 offset:55296
	ds_read_b128 v[220:223], v162 offset:56320
	global_load_lds_dwordx4 v128, s[72:73]
	s_add_u32 m0, s35, 0xa000
	s_nop 0
	global_load_lds_dwordx4 v130, s[72:73]
	s_add_u32 s72, s72, 0x80
	s_addc_u32 s73, s73, 0
	s_barrier
	s_waitcnt lgkmcnt(0)
	s_setprio 1
	v_mfma_f32_16x16x32_bf16 v[60:63], v[176:179], v[192:195], v[60:63]
	v_mfma_f32_16x16x32_bf16 v[56:59], v[184:187], v[192:195], v[56:59]
	v_mfma_f32_16x16x32_bf16 v[52:55], v[176:179], v[200:203], v[52:55]
	v_mfma_f32_16x16x32_bf16 v[48:51], v[184:187], v[200:203], v[48:51]
	v_mfma_f32_16x16x32_bf16 v[44:47], v[176:179], v[208:211], v[44:47]
	v_mfma_f32_16x16x32_bf16 v[40:43], v[184:187], v[208:211], v[40:43]
	v_mfma_f32_16x16x32_bf16 v[36:39], v[176:179], v[216:219], v[36:39]
	v_mfma_f32_16x16x32_bf16 v[32:35], v[184:187], v[216:219], v[32:35]
	v_mfma_f32_16x16x32_bf16 v[60:63], v[180:183], v[196:199], v[60:63]
	v_mfma_f32_16x16x32_bf16 v[56:59], v[188:191], v[196:199], v[56:59]
	v_mfma_f32_16x16x32_bf16 v[52:55], v[180:183], v[204:207], v[52:55]
	v_mfma_f32_16x16x32_bf16 v[48:51], v[188:191], v[204:207], v[48:51]
	v_mfma_f32_16x16x32_bf16 v[44:47], v[180:183], v[212:215], v[44:47]
	v_mfma_f32_16x16x32_bf16 v[40:43], v[188:191], v[212:215], v[40:43]
	v_mfma_f32_16x16x32_bf16 v[36:39], v[180:183], v[220:223], v[36:39]
	v_mfma_f32_16x16x32_bf16 v[32:35], v[188:191], v[220:223], v[32:35]
	s_setprio 0
	s_barrier
	s_add_u32 m0, s35, 0x1c000
	s_nop 0
	global_load_lds_dwordx4 v128, s[78:79]
	s_add_u32 m0, s35, 0x1e000
	s_nop 0
	global_load_lds_dwordx4 v130, s[78:79]
	s_add_u32 s78, s78, 0x80
	s_addc_u32 s79, s79, 0
	s_waitcnt vmcnt(6)
	s_barrier
	s_setprio 1
	v_mfma_f32_16x16x32_bf16 v[28:31], v[224:227], v[192:195], v[28:31]
	v_mfma_f32_16x16x32_bf16 v[24:27], v[232:235], v[192:195], v[24:27]
	v_mfma_f32_16x16x32_bf16 v[20:23], v[224:227], v[200:203], v[20:23]
	v_mfma_f32_16x16x32_bf16 v[16:19], v[232:235], v[200:203], v[16:19]
	v_mfma_f32_16x16x32_bf16 v[12:15], v[224:227], v[208:211], v[12:15]
	v_mfma_f32_16x16x32_bf16 v[8:11], v[232:235], v[208:211], v[8:11]
	v_mfma_f32_16x16x32_bf16 v[4:7], v[224:227], v[216:219], v[4:7]
	v_mfma_f32_16x16x32_bf16 v[0:3], v[232:235], v[216:219], v[0:3]
	v_mfma_f32_16x16x32_bf16 v[28:31], v[228:231], v[196:199], v[28:31]
	v_mfma_f32_16x16x32_bf16 v[24:27], v[236:239], v[196:199], v[24:27]
	v_mfma_f32_16x16x32_bf16 v[20:23], v[228:231], v[204:207], v[20:23]
	v_mfma_f32_16x16x32_bf16 v[16:19], v[236:239], v[204:207], v[16:19]
	v_mfma_f32_16x16x32_bf16 v[12:15], v[228:231], v[212:215], v[12:15]
	v_mfma_f32_16x16x32_bf16 v[8:11], v[236:239], v[212:215], v[8:11]
	v_mfma_f32_16x16x32_bf16 v[4:7], v[228:231], v[220:223], v[4:7]
	v_mfma_f32_16x16x32_bf16 v[0:3], v[236:239], v[220:223], v[0:3]
	s_setprio 0
	s_cmp_lt_u32 s34, s3
	s_barrier
	s_cbranch_scc1 .LBB0_187
	s_mov_b64 s[72:73], 0x80
	s_mov_b64 s[76:77], 0x100
	s_mov_b64 s[78:79], 0x180
	s_add_i32 s66, s2, -1
	s_lshl_b64 s[2:3], s[66:67], 7
	s_add_u32 s2, s54, s2
	s_addc_u32 s3, s55, s3
	v_readfirstlane_b32 s34, v174
	v_lshl_add_u64 v[150:151], s[2:3], 0, v[128:129]
	s_mov_b32 m0, s34
	v_lshl_add_u64 v[130:131], s[2:3], 0, v[130:131]
	v_readfirstlane_b32 s2, v175
	ds_read_b128 v[132:135], v164
	ds_read_b128 v[136:139], v164 offset:1024
	ds_read_b128 v[140:143], v164 offset:2048
	ds_read_b128 v[144:147], v164 offset:3072
	ds_read_b128 v[158:161], v162
	ds_read_b128 v[166:169], v162 offset:1024
	ds_read_b128 v[170:173], v162 offset:2048
	ds_read_b128 v[176:179], v162 offset:3072
	ds_read_b128 v[180:183], v162 offset:4096
	ds_read_b128 v[184:187], v162 offset:5120
	ds_read_b128 v[188:191], v162 offset:6144
	ds_read_b128 v[192:195], v162 offset:7168
	global_load_lds_dwordx4 v[150:151], off
	s_mov_b32 m0, s2
	s_nop 0
	global_load_lds_dwordx4 v[130:131], off
	s_barrier
	s_waitcnt lgkmcnt(0)
	s_setprio 1
	s_waitcnt lgkmcnt(0)
	v_mfma_f32_16x16x32_bf16 v[124:127], v[132:135], v[158:161], v[124:127]
	v_mfma_f32_16x16x32_bf16 v[120:123], v[140:143], v[158:161], v[120:123]
	v_mfma_f32_16x16x32_bf16 v[116:119], v[132:135], v[170:173], v[116:119]
	v_mfma_f32_16x16x32_bf16 v[112:115], v[140:143], v[170:173], v[112:115]
	v_mfma_f32_16x16x32_bf16 v[100:103], v[132:135], v[188:191], v[100:103]
	v_mfma_f32_16x16x32_bf16 v[96:99], v[140:143], v[188:191], v[96:99]
	v_mfma_f32_16x16x32_bf16 v[124:127], v[136:139], v[166:169], v[124:127]
	v_mfma_f32_16x16x32_bf16 v[120:123], v[144:147], v[166:169], v[120:123]
	v_mfma_f32_16x16x32_bf16 v[116:119], v[136:139], v[176:179], v[116:119]
	v_mfma_f32_16x16x32_bf16 v[112:115], v[144:147], v[176:179], v[112:115]
	v_mfma_f32_16x16x32_bf16 v[108:111], v[132:135], v[180:183], v[108:111]
	v_mfma_f32_16x16x32_bf16 v[104:107], v[140:143], v[180:183], v[104:107]
	v_mfma_f32_16x16x32_bf16 v[100:103], v[136:139], v[192:195], v[100:103]
	v_mfma_f32_16x16x32_bf16 v[96:99], v[144:147], v[192:195], v[96:99]
	v_mfma_f32_16x16x32_bf16 v[196:199], v[136:139], v[184:187], v[108:111]
	v_mfma_f32_16x16x32_bf16 v[200:203], v[144:147], v[184:187], v[104:107]
	s_setprio 0
	s_barrier
	s_nop 1
	ds_read_b128 v[104:107], v164 offset:16384
	ds_read_b128 v[108:111], v164 offset:17408
	ds_read_b128 v[204:207], v164 offset:18432
	ds_read_b128 v[208:211], v164 offset:19456
	s_barrier
	s_waitcnt lgkmcnt(0)
	s_setprio 1
	s_waitcnt lgkmcnt(0)
	v_mfma_f32_16x16x32_bf16 v[84:87], v[104:107], v[170:173], v[84:87]
	v_mfma_f32_16x16x32_bf16 v[80:83], v[204:207], v[170:173], v[80:83]
	v_mfma_f32_16x16x32_bf16 v[68:71], v[104:107], v[188:191], v[68:71]
	v_mfma_f32_16x16x32_bf16 v[64:67], v[204:207], v[188:191], v[64:67]
	v_mfma_f32_16x16x32_bf16 v[92:95], v[104:107], v[158:161], v[92:95]
	v_mfma_f32_16x16x32_bf16 v[88:91], v[204:207], v[158:161], v[88:91]
	v_mfma_f32_16x16x32_bf16 v[84:87], v[108:111], v[176:179], v[84:87]
	v_mfma_f32_16x16x32_bf16 v[80:83], v[208:211], v[176:179], v[80:83]
	v_mfma_f32_16x16x32_bf16 v[76:79], v[104:107], v[180:183], v[76:79]
	v_mfma_f32_16x16x32_bf16 v[72:75], v[204:207], v[180:183], v[72:75]
	v_mfma_f32_16x16x32_bf16 v[68:71], v[108:111], v[192:195], v[68:71]
	v_mfma_f32_16x16x32_bf16 v[64:67], v[208:211], v[192:195], v[64:67]
	v_mfma_f32_16x16x32_bf16 v[212:215], v[108:111], v[166:169], v[92:95]
	v_mfma_f32_16x16x32_bf16 v[158:161], v[208:211], v[166:169], v[88:91]
	v_mfma_f32_16x16x32_bf16 v[166:169], v[108:111], v[184:187], v[76:79]
	v_mfma_f32_16x16x32_bf16 v[170:173], v[208:211], v[184:187], v[72:75]
	s_setprio 0
	s_barrier
	s_nop 0
	ds_read_b128 v[72:75], v162 offset:16384
	ds_read_b128 v[76:79], v162 offset:17408
	ds_read_b128 v[88:91], v162 offset:18432
	ds_read_b128 v[92:95], v162 offset:19456
	ds_read_b128 v[174:177], v162 offset:20480
	ds_read_b128 v[178:181], v162 offset:21504
	ds_read_b128 v[182:185], v162 offset:22528
	ds_read_b128 v[186:189], v162 offset:23552
	s_waitcnt vmcnt(4)
	s_barrier
	s_waitcnt lgkmcnt(0)
	s_setprio 1
	s_waitcnt lgkmcnt(0)
	v_mfma_f32_16x16x32_bf16 v[60:63], v[132:135], v[72:75], v[60:63]
	v_mfma_f32_16x16x32_bf16 v[56:59], v[140:143], v[72:75], v[56:59]
	v_mfma_f32_16x16x32_bf16 v[52:55], v[132:135], v[88:91], v[52:55]
	v_mfma_f32_16x16x32_bf16 v[48:51], v[140:143], v[88:91], v[48:51]
	v_mfma_f32_16x16x32_bf16 v[36:39], v[132:135], v[182:185], v[36:39]
	v_mfma_f32_16x16x32_bf16 v[32:35], v[140:143], v[182:185], v[32:35]
	v_mfma_f32_16x16x32_bf16 v[60:63], v[136:139], v[76:79], v[60:63]
	v_mfma_f32_16x16x32_bf16 v[56:59], v[144:147], v[76:79], v[56:59]
	v_mfma_f32_16x16x32_bf16 v[52:55], v[136:139], v[92:95], v[52:55]
	v_mfma_f32_16x16x32_bf16 v[48:51], v[144:147], v[92:95], v[48:51]
	v_mfma_f32_16x16x32_bf16 v[44:47], v[132:135], v[174:177], v[44:47]
	v_mfma_f32_16x16x32_bf16 v[40:43], v[140:143], v[174:177], v[40:43]
	v_mfma_f32_16x16x32_bf16 v[36:39], v[136:139], v[186:189], v[36:39]
	v_mfma_f32_16x16x32_bf16 v[32:35], v[144:147], v[186:189], v[32:35]
	v_mfma_f32_16x16x32_bf16 v[190:193], v[136:139], v[178:181], v[44:47]
	v_mfma_f32_16x16x32_bf16 v[216:219], v[144:147], v[178:181], v[40:43]
	s_setprio 0
	s_setprio 1
	v_mfma_f32_16x16x32_bf16 v[20:23], v[104:107], v[88:91], v[20:23]
	v_mfma_f32_16x16x32_bf16 v[16:19], v[204:207], v[88:91], v[16:19]
	v_mfma_f32_16x16x32_bf16 v[4:7], v[104:107], v[182:185], v[4:7]
	v_mfma_f32_16x16x32_bf16 v[0:3], v[204:207], v[182:185], v[0:3]
	v_mfma_f32_16x16x32_bf16 v[28:31], v[104:107], v[72:75], v[28:31]
	v_mfma_f32_16x16x32_bf16 v[24:27], v[204:207], v[72:75], v[24:27]
	v_mfma_f32_16x16x32_bf16 v[20:23], v[108:111], v[92:95], v[20:23]
	v_mfma_f32_16x16x32_bf16 v[16:19], v[208:211], v[92:95], v[16:19]
	v_mfma_f32_16x16x32_bf16 v[12:15], v[104:107], v[174:177], v[12:15]
	v_mfma_f32_16x16x32_bf16 v[8:11], v[204:207], v[174:177], v[8:11]
	v_mfma_f32_16x16x32_bf16 v[4:7], v[108:111], v[186:189], v[4:7]
	v_mfma_f32_16x16x32_bf16 v[0:3], v[208:211], v[186:189], v[0:3]
	v_mfma_f32_16x16x32_bf16 v[130:133], v[108:111], v[76:79], v[28:31]
	v_mfma_f32_16x16x32_bf16 v[134:137], v[208:211], v[76:79], v[24:27]
	v_mfma_f32_16x16x32_bf16 v[138:141], v[108:111], v[178:181], v[12:15]
	v_mfma_f32_16x16x32_bf16 v[142:145], v[208:211], v[178:181], v[8:11]
	s_setprio 0
	s_barrier
	s_nop 0
	ds_read_b128 v[8:11], v164 offset:32768
	ds_read_b128 v[12:15], v164 offset:33792
	ds_read_b128 v[174:177], v164 offset:34816
	ds_read_b128 v[178:181], v164 offset:35840
	ds_read_b128 v[24:27], v162 offset:32768
	ds_read_b128 v[28:31], v162 offset:33792
	ds_read_b128 v[40:43], v162 offset:34816
	ds_read_b128 v[44:47], v162 offset:35840
	ds_read_b128 v[182:185], v162 offset:36864
	ds_read_b128 v[186:189], v162 offset:37888
	ds_read_b128 v[204:207], v162 offset:38912
	ds_read_b128 v[208:211], v162 offset:39936
	s_waitcnt vmcnt(2)
	s_barrier
	s_waitcnt lgkmcnt(0)
	s_setprio 1
	s_waitcnt lgkmcnt(0)
	v_mfma_f32_16x16x32_bf16 v[72:75], v[8:11], v[24:27], v[124:127]
	v_mfma_f32_16x16x32_bf16 v[124:127], v[12:15], v[28:31], v[72:75]
	v_mfma_f32_16x16x32_bf16 v[72:75], v[174:177], v[24:27], v[120:123]
	v_mfma_f32_16x16x32_bf16 v[120:123], v[178:181], v[28:31], v[72:75]
	v_mfma_f32_16x16x32_bf16 v[72:75], v[8:11], v[40:43], v[116:119]
	v_mfma_f32_16x16x32_bf16 v[108:111], v[12:15], v[44:47], v[72:75]
	v_mfma_f32_16x16x32_bf16 v[72:75], v[174:177], v[40:43], v[112:115]
	v_mfma_f32_16x16x32_bf16 v[104:107], v[178:181], v[44:47], v[72:75]
	v_mfma_f32_16x16x32_bf16 v[72:75], v[8:11], v[182:185], v[196:199]
	v_mfma_f32_16x16x32_bf16 v[92:95], v[12:15], v[186:189], v[72:75]
	v_mfma_f32_16x16x32_bf16 v[72:75], v[174:177], v[182:185], v[200:203]
	v_mfma_f32_16x16x32_bf16 v[88:91], v[178:181], v[186:189], v[72:75]
	v_mfma_f32_16x16x32_bf16 v[72:75], v[8:11], v[204:207], v[100:103]
	v_mfma_f32_16x16x32_bf16 v[76:79], v[12:15], v[208:211], v[72:75]
	v_mfma_f32_16x16x32_bf16 v[72:75], v[174:177], v[204:207], v[96:99]
	v_mfma_f32_16x16x32_bf16 v[72:75], v[178:181], v[208:211], v[72:75]
	s_setprio 0
	s_barrier
	ds_read_b128 v[194:197], v164 offset:49152
	ds_read_b128 v[198:201], v164 offset:50176
	ds_read_b128 v[220:223], v164 offset:51200
	ds_read_b128 v[224:227], v164 offset:52224
	s_waitcnt vmcnt(0)
	s_barrier
	s_waitcnt lgkmcnt(0)
	s_setprio 1
	s_waitcnt lgkmcnt(0)
	v_mfma_f32_16x16x32_bf16 v[96:99], v[194:197], v[24:27], v[212:215]
	v_mfma_f32_16x16x32_bf16 v[24:27], v[220:223], v[24:27], v[158:161]
	v_mfma_f32_16x16x32_bf16 v[112:115], v[224:227], v[28:31], v[24:27]
	v_mfma_f32_16x16x32_bf16 v[24:27], v[194:197], v[40:43], v[84:87]
	v_mfma_f32_16x16x32_bf16 v[100:103], v[198:201], v[44:47], v[24:27]
	v_mfma_f32_16x16x32_bf16 v[24:27], v[220:223], v[40:43], v[80:83]
	v_mfma_f32_16x16x32_bf16 v[116:119], v[198:201], v[28:31], v[96:99]
	v_mfma_f32_16x16x32_bf16 v[96:99], v[224:227], v[44:47], v[24:27]
	v_mfma_f32_16x16x32_bf16 v[24:27], v[194:197], v[182:185], v[166:169]
	v_mfma_f32_16x16x32_bf16 v[84:87], v[198:201], v[186:189], v[24:27]
	v_mfma_f32_16x16x32_bf16 v[24:27], v[220:223], v[182:185], v[170:173]
	v_mfma_f32_16x16x32_bf16 v[80:83], v[224:227], v[186:189], v[24:27]
	v_mfma_f32_16x16x32_bf16 v[24:27], v[194:197], v[204:207], v[68:71]
	v_mfma_f32_16x16x32_bf16 v[68:71], v[198:201], v[208:211], v[24:27]
	v_mfma_f32_16x16x32_bf16 v[24:27], v[220:223], v[204:207], v[64:67]
	v_mfma_f32_16x16x32_bf16 v[64:67], v[224:227], v[208:211], v[24:27]
	s_setprio 0
	s_barrier
	ds_read_b128 v[158:161], v162 offset:49152
	ds_read_b128 v[164:167], v162 offset:50176
	ds_read_b128 v[168:171], v162 offset:51200
	ds_read_b128 v[182:185], v162 offset:52224
	ds_read_b128 v[186:189], v162 offset:53248
	ds_read_b128 v[202:205], v162 offset:54272
	ds_read_b128 v[206:209], v162 offset:55296
	ds_read_b128 v[210:213], v162 offset:56320
	s_barrier
	s_waitcnt lgkmcnt(0)
	s_setprio 1
	s_waitcnt lgkmcnt(0)
	v_mfma_f32_16x16x32_bf16 v[24:27], v[8:11], v[158:161], v[60:63]
	v_mfma_f32_16x16x32_bf16 v[60:63], v[12:15], v[164:167], v[24:27]
	v_mfma_f32_16x16x32_bf16 v[24:27], v[174:177], v[158:161], v[56:59]
	v_mfma_f32_16x16x32_bf16 v[56:59], v[178:181], v[164:167], v[24:27]
	v_mfma_f32_16x16x32_bf16 v[24:27], v[8:11], v[168:171], v[52:55]
	v_mfma_f32_16x16x32_bf16 v[44:47], v[12:15], v[182:185], v[24:27]
	v_mfma_f32_16x16x32_bf16 v[24:27], v[174:177], v[168:171], v[48:51]
	v_mfma_f32_16x16x32_bf16 v[40:43], v[178:181], v[182:185], v[24:27]
	v_mfma_f32_16x16x32_bf16 v[24:27], v[8:11], v[186:189], v[190:193]
	v_mfma_f32_16x16x32_bf16 v[8:11], v[8:11], v[206:209], v[36:39]
	v_mfma_f32_16x16x32_bf16 v[28:31], v[12:15], v[202:205], v[24:27]
	v_mfma_f32_16x16x32_bf16 v[24:27], v[174:177], v[186:189], v[216:219]
	v_mfma_f32_16x16x32_bf16 v[12:15], v[12:15], v[210:213], v[8:11]
	v_mfma_f32_16x16x32_bf16 v[8:11], v[174:177], v[206:209], v[32:35]
	v_mfma_f32_16x16x32_bf16 v[24:27], v[178:181], v[202:205], v[24:27]
	v_mfma_f32_16x16x32_bf16 v[8:11], v[178:181], v[210:213], v[8:11]
	s_setprio 0
	s_setprio 1
	v_mfma_f32_16x16x32_bf16 v[32:35], v[194:197], v[158:161], v[130:133]
	v_mfma_f32_16x16x32_bf16 v[52:55], v[198:201], v[164:167], v[32:35]
	v_mfma_f32_16x16x32_bf16 v[32:35], v[220:223], v[158:161], v[134:137]
	v_mfma_f32_16x16x32_bf16 v[16:19], v[220:223], v[168:171], v[16:19]
	v_mfma_f32_16x16x32_bf16 v[48:51], v[224:227], v[164:167], v[32:35]
	v_mfma_f32_16x16x32_bf16 v[20:23], v[194:197], v[168:171], v[20:23]
	v_mfma_f32_16x16x32_bf16 v[32:35], v[224:227], v[182:185], v[16:19]
	v_mfma_f32_16x16x32_bf16 v[16:19], v[194:197], v[186:189], v[138:141]
	v_mfma_f32_16x16x32_bf16 v[36:39], v[198:201], v[182:185], v[20:23]
	v_mfma_f32_16x16x32_bf16 v[20:23], v[198:201], v[202:205], v[16:19]
	v_mfma_f32_16x16x32_bf16 v[16:19], v[220:223], v[186:189], v[142:145]
	v_mfma_f32_16x16x32_bf16 v[4:7], v[194:197], v[206:209], v[4:7]
	v_mfma_f32_16x16x32_bf16 v[0:3], v[220:223], v[206:209], v[0:3]
	v_mfma_f32_16x16x32_bf16 v[16:19], v[224:227], v[202:205], v[16:19]
	v_mfma_f32_16x16x32_bf16 v[4:7], v[198:201], v[210:213], v[4:7]
	v_mfma_f32_16x16x32_bf16 v[0:3], v[224:227], v[210:213], v[0:3]
	s_setprio 0
	s_movk_i32 s2, 0x100
	v_cmp_gt_u32_e32 vcc, s2, v157
	s_barrier
	s_and_saveexec_b64 s[2:3], vcc
	s_cbranch_execz .LBB0_190
	s_barrier
